# P7 epilogue: final-output stores without the nt hint (plain stores merge into full lines in L2)
# speedup vs baseline: 1.0140x; 1.0069x over previous
;     __device__ __forceinline__ void operator()(const pg8::f32x4 (&acc)[2][2][4][2], const pg8::Unit& u, int wr, int wc, int fr, int fq) const {
;         const int b = u.pm >> 4;
; #pragma unroll
;         for (int bj = 0; bj < 2; ++bj) { const int c0 = u.pn * 256 + bj * 128 + wc * 32 + 8 * fq; const float* g2p = e.mod + (size_t)b * NMOD + 5 * DM + c0; const f32x4 ga = *(const f32x4*)g2p, gb = *(const f32x4*)(g2p + 4);
; #pragma unroll
;             for (int ai = 0; ai < 2; ++ai)
; #pragma unroll
;                 for (int m = 0; m < 4; ++m) { ACC8(v, ai, bj, m); const size_t off = (size_t)(u.pm * 256 + ai * 128 + wr * 64 + m * 16 + fr) * DM + c0;
;                     f32x4 xa = __builtin_nontemporal_load((const f32x4*)(e.out + off)), xc = __builtin_nontemporal_load((const f32x4*)(e.out + off + 4));
; #pragma unroll
;                     for (int i = 0; i < 4; ++i) { xa[i] += ga[i] * v[i]; xc[i] += gb[i] * v[4 + i]; }
;                     float* dst = e.dump ? e.dump + (off & (size_t)0x7ffff8) : e.out + off;
;                     __builtin_nontemporal_store(xa, (f32x4*)dst); __builtin_nontemporal_store(xc, (f32x4*)(dst + 4)); }
.LBB9_856:
	s_ashr_i32 s14, s37, 4
	v_lshl_add_u32 v166, s37, 8, v170
	s_mul_hi_i32 s15, s14, 0x6000
	s_mulk_i32 s14, 0x6000
	v_ashrrev_i32_e32 v167, 31, v166
	s_add_u32 s14, s90, s14
	v_lshlrev_b64 v[152:153], 12, v[166:167]
	v_or_b32_e32 v154, 16, v166
	v_or_b32_e32 v156, 32, v166
	v_or_b32_e32 v158, 48, v166
	v_add_u32_e32 v160, 0x80, v166
	v_add_u32_e32 v162, 0x90, v166
	v_add_u32_e32 v164, 0xa0, v166
	v_add_u32_e32 v166, 0xb0, v166
	v_lshl_or_b32 v168, s38, 8, v172
	s_addc_u32 s15, s91, s15
	v_ashrrev_i32_e32 v155, 31, v154
	v_ashrrev_i32_e32 v157, 31, v156
	v_ashrrev_i32_e32 v159, 31, v158
	v_ashrrev_i32_e32 v161, 31, v160
	v_ashrrev_i32_e32 v163, 31, v162
	v_ashrrev_i32_e32 v165, 31, v164
	v_ashrrev_i32_e32 v167, 31, v166
	s_add_u32 s14, s14, 0x1f45000
	v_ashrrev_i32_e32 v169, 31, v168
	v_lshlrev_b64 v[154:155], 12, v[154:155]
	v_lshlrev_b64 v[156:157], 12, v[156:157]
	v_lshlrev_b64 v[158:159], 12, v[158:159]
	v_lshlrev_b64 v[160:161], 12, v[160:161]
	v_lshlrev_b64 v[162:163], 12, v[162:163]
	v_lshlrev_b64 v[164:165], 12, v[164:165]
	v_lshlrev_b64 v[166:167], 12, v[166:167]
	s_addc_u32 s15, s15, 0
	v_lshlrev_b64 v[232:233], 2, v[168:169]
	v_lshl_add_u64 v[152:153], s[88:89], 0, v[152:153]
	v_lshl_add_u64 v[154:155], s[88:89], 0, v[154:155]
	v_lshl_add_u64 v[156:157], s[88:89], 0, v[156:157]
	v_lshl_add_u64 v[158:159], s[88:89], 0, v[158:159]
	v_lshl_add_u64 v[160:161], s[88:89], 0, v[160:161]
	v_lshl_add_u64 v[162:163], s[88:89], 0, v[162:163]
	v_lshl_add_u64 v[164:165], s[88:89], 0, v[164:165]
	v_lshl_add_u64 v[166:167], s[88:89], 0, v[166:167]
	v_lshl_add_u64 v[132:133], s[14:15], 0, v[232:233]
	v_lshl_add_u64 v[152:153], v[152:153], 0, v[232:233]
	v_lshl_add_u64 v[154:155], v[154:155], 0, v[232:233]
	v_lshl_add_u64 v[156:157], v[156:157], 0, v[232:233]
	v_lshl_add_u64 v[158:159], v[158:159], 0, v[232:233]
	v_lshl_add_u64 v[160:161], v[160:161], 0, v[232:233]
	v_lshl_add_u64 v[162:163], v[162:163], 0, v[232:233]
	v_lshl_add_u64 v[164:165], v[164:165], 0, v[232:233]
	v_lshl_add_u64 v[166:167], v[166:167], 0, v[232:233]
	global_load_dwordx4 v[128:131], v[132:133], off offset:16
	s_nop 0
	global_load_dwordx4 v[132:135], v[132:133], off
	s_nop 0
	global_load_dwordx4 v[176:179], v[152:153], off offset:16 nt
	global_load_dwordx4 v[180:183], v[152:153], off nt
	global_load_dwordx4 v[184:187], v[154:155], off offset:16 nt
	global_load_dwordx4 v[188:191], v[154:155], off nt
	global_load_dwordx4 v[192:195], v[156:157], off offset:16 nt
	global_load_dwordx4 v[196:199], v[156:157], off nt
	global_load_dwordx4 v[200:203], v[158:159], off nt
	global_load_dwordx4 v[204:207], v[158:159], off offset:16 nt
	global_load_dwordx4 v[208:211], v[160:161], off offset:16 nt
	global_load_dwordx4 v[212:215], v[160:161], off nt
	global_load_dwordx4 v[216:219], v[162:163], off offset:16 nt
	global_load_dwordx4 v[220:223], v[162:163], off nt
	global_load_dwordx4 v[224:227], v[164:165], off offset:16 nt
	global_load_dwordx4 v[228:231], v[164:165], off nt
	global_load_dwordx4 v[232:235], v[166:167], off nt
	global_load_dwordx4 v[236:239], v[166:167], off offset:16 nt
	s_and_b64 vcc, exec, s[0:1]
	s_mov_b64 s[0:1], -1
	s_waitcnt vmcnt(0)
;     __device__ __forceinline__ void operator()(const pg8::f32x4 (&acc)[2][2][4][2], const pg8::Unit& u, int wr, int wc, int fr, int fq) const {
;         const int b = u.pm >> 4;
; #pragma unroll
;         for (int bj = 0; bj < 2; ++bj) { const int c0 = u.pn * 256 + bj * 128 + wc * 32 + 8 * fq; const float* g2p = e.mod + (size_t)b * NMOD + 5 * DM + c0; const f32x4 ga = *(const f32x4*)g2p, gb = *(const f32x4*)(g2p + 4);
; #pragma unroll
;             for (int ai = 0; ai < 2; ++ai)
; #pragma unroll
;                 for (int m = 0; m < 4; ++m) { ACC8(v, ai, bj, m); const size_t off = (size_t)(u.pm * 256 + ai * 128 + wr * 64 + m * 16 + fr) * DM + c0;
;                     f32x4 xa = __builtin_nontemporal_load((const f32x4*)(e.out + off)), xc = __builtin_nontemporal_load((const f32x4*)(e.out + off + 4));
; #pragma unroll
;                     for (int i = 0; i < 4; ++i) { xa[i] += ga[i] * v[i]; xc[i] += gb[i] * v[4 + i]; }
;                     float* dst = e.dump ? e.dump + (off & (size_t)0x7ffff8) : e.out + off;
;                     __builtin_nontemporal_store(xa, (f32x4*)dst); __builtin_nontemporal_store(xc, (f32x4*)(dst + 4)); }
	v_pk_fma_f32 v[122:123], v[122:123], v[130:131], v[178:179]
	v_pk_fma_f32 v[126:127], v[126:127], v[134:135], v[182:183]
	v_pk_fma_f32 v[124:125], v[124:125], v[132:133], v[180:181]
	v_pk_fma_f32 v[102:103], v[102:103], v[134:135], v[202:203]
	v_pk_fma_f32 v[100:101], v[100:101], v[132:133], v[200:201]
	v_pk_fma_f32 v[94:95], v[94:95], v[134:135], v[214:215]
	v_pk_fma_f32 v[92:93], v[92:93], v[132:133], v[212:213]
	v_pk_fma_f32 v[86:87], v[86:87], v[134:135], v[222:223]
	v_pk_fma_f32 v[84:85], v[84:85], v[132:133], v[220:221]
	v_pk_fma_f32 v[78:79], v[78:79], v[134:135], v[230:231]
	v_pk_fma_f32 v[76:77], v[76:77], v[132:133], v[228:229]
	v_pk_fma_f32 v[70:71], v[70:71], v[134:135], v[234:235]
	v_pk_fma_f32 v[68:69], v[68:69], v[132:133], v[232:233]
	v_pk_fma_f32 v[64:65], v[64:65], v[128:129], v[236:237]
	v_pk_fma_f32 v[120:121], v[120:121], v[128:129], v[176:177]
	v_pk_fma_f32 v[118:119], v[118:119], v[134:135], v[190:191]
	v_pk_fma_f32 v[116:117], v[116:117], v[132:133], v[188:189]
	v_pk_fma_f32 v[114:115], v[114:115], v[130:131], v[186:187]
	v_pk_fma_f32 v[112:113], v[112:113], v[128:129], v[184:185]
	v_pk_fma_f32 v[110:111], v[110:111], v[134:135], v[198:199]
	v_pk_fma_f32 v[108:109], v[108:109], v[132:133], v[196:197]
	v_pk_fma_f32 v[106:107], v[106:107], v[130:131], v[194:195]
	v_pk_fma_f32 v[104:105], v[104:105], v[128:129], v[192:193]
	global_store_dwordx4 v[152:153], v[124:127], off
	global_store_dwordx4 v[152:153], v[120:123], off offset:16
	global_store_dwordx4 v[154:155], v[116:119], off
	global_store_dwordx4 v[154:155], v[112:115], off offset:16
	global_store_dwordx4 v[156:157], v[108:111], off
	global_store_dwordx4 v[156:157], v[104:107], off offset:16
	v_pk_fma_f32 v[98:99], v[98:99], v[130:131], v[206:207]
	v_pk_fma_f32 v[96:97], v[96:97], v[128:129], v[204:205]
	global_store_dwordx4 v[158:159], v[100:103], off
	global_store_dwordx4 v[158:159], v[96:99], off offset:16
	v_pk_fma_f32 v[90:91], v[90:91], v[130:131], v[210:211]
	v_pk_fma_f32 v[88:89], v[88:89], v[128:129], v[208:209]
	global_store_dwordx4 v[160:161], v[92:95], off
	global_store_dwordx4 v[160:161], v[88:91], off offset:16
	v_pk_fma_f32 v[82:83], v[82:83], v[130:131], v[218:219]
	v_pk_fma_f32 v[80:81], v[80:81], v[128:129], v[216:217]
	global_store_dwordx4 v[162:163], v[84:87], off
	global_store_dwordx4 v[162:163], v[80:83], off offset:16
	v_pk_fma_f32 v[74:75], v[74:75], v[130:131], v[226:227]
	v_pk_fma_f32 v[72:73], v[72:73], v[128:129], v[224:225]
	global_store_dwordx4 v[164:165], v[76:79], off
	global_store_dwordx4 v[164:165], v[72:75], off offset:16
	v_pk_fma_f32 v[66:67], v[66:67], v[130:131], v[238:239]
	global_store_dwordx4 v[166:167], v[68:71], off
	global_store_dwordx4 v[166:167], v[64:67], off offset:16
	s_nop 1
	v_or_b32_e32 v64, 0x80, v168
	v_ashrrev_i32_e32 v65, 31, v64
	v_lshl_add_u64 v[88:89], v[64:65], 2, s[14:15]
	global_load_dwordx4 v[64:67], v[152:153], off offset:512 nt
	global_load_dwordx4 v[68:71], v[88:89], off
	global_load_dwordx4 v[72:75], v[88:89], off offset:16
	global_load_dwordx4 v[76:79], v[152:153], off offset:528 nt
	global_load_dwordx4 v[80:83], v[154:155], off offset:512 nt
	global_load_dwordx4 v[84:87], v[154:155], off offset:528 nt
	s_nop 0
	global_load_dwordx4 v[88:91], v[156:157], off offset:512 nt
	global_load_dwordx4 v[92:95], v[156:157], off offset:528 nt
	global_load_dwordx4 v[96:99], v[158:159], off offset:512 nt
	global_load_dwordx4 v[100:103], v[158:159], off offset:528 nt
	global_load_dwordx4 v[104:107], v[160:161], off offset:512 nt
	global_load_dwordx4 v[108:111], v[160:161], off offset:528 nt
	global_load_dwordx4 v[112:115], v[162:163], off offset:512 nt
	global_load_dwordx4 v[116:119], v[162:163], off offset:528 nt
	global_load_dwordx4 v[120:123], v[164:165], off offset:512 nt
	global_load_dwordx4 v[124:127], v[164:165], off offset:528 nt
	global_load_dwordx4 v[128:131], v[166:167], off offset:512 nt
	global_load_dwordx4 v[132:135], v[166:167], off offset:528 nt
	s_waitcnt vmcnt(16)
	v_pk_fma_f32 v[62:63], v[62:63], v[70:71], v[66:67]
	v_pk_fma_f32 v[60:61], v[60:61], v[68:69], v[64:65]
	s_waitcnt vmcnt(14)
	v_pk_fma_f32 v[58:59], v[58:59], v[74:75], v[78:79]
	v_pk_fma_f32 v[56:57], v[56:57], v[72:73], v[76:77]
	s_waitcnt vmcnt(13)
	v_pk_fma_f32 v[54:55], v[54:55], v[70:71], v[82:83]
	v_pk_fma_f32 v[52:53], v[52:53], v[68:69], v[80:81]
	s_waitcnt vmcnt(12)
	v_pk_fma_f32 v[50:51], v[50:51], v[74:75], v[86:87]
	v_pk_fma_f32 v[48:49], v[48:49], v[72:73], v[84:85]
	s_waitcnt vmcnt(11)
	v_pk_fma_f32 v[46:47], v[46:47], v[70:71], v[90:91]
	v_pk_fma_f32 v[44:45], v[44:45], v[68:69], v[88:89]
	s_waitcnt vmcnt(10)
	v_pk_fma_f32 v[42:43], v[42:43], v[74:75], v[94:95]
	v_pk_fma_f32 v[40:41], v[40:41], v[72:73], v[92:93]
	s_waitcnt vmcnt(5)
	v_pk_fma_f32 v[22:23], v[22:23], v[70:71], v[114:115]
	v_pk_fma_f32 v[20:21], v[20:21], v[68:69], v[112:113]
	s_waitcnt vmcnt(3)
	v_pk_fma_f32 v[14:15], v[14:15], v[70:71], v[122:123]
	v_pk_fma_f32 v[12:13], v[12:13], v[68:69], v[120:121]
	s_waitcnt vmcnt(1)
	v_pk_fma_f32 v[6:7], v[6:7], v[70:71], v[130:131]
	v_pk_fma_f32 v[4:5], v[4:5], v[68:69], v[128:129]
	v_pk_fma_f32 v[38:39], v[38:39], v[70:71], v[98:99]
	v_pk_fma_f32 v[36:37], v[36:37], v[68:69], v[96:97]
	v_pk_fma_f32 v[34:35], v[34:35], v[74:75], v[102:103]
	v_pk_fma_f32 v[32:33], v[32:33], v[72:73], v[100:101]
	v_pk_fma_f32 v[30:31], v[30:31], v[70:71], v[106:107]
	v_pk_fma_f32 v[28:29], v[28:29], v[68:69], v[104:105]
	v_pk_fma_f32 v[26:27], v[26:27], v[74:75], v[110:111]
	v_pk_fma_f32 v[24:25], v[24:25], v[72:73], v[108:109]
	v_pk_fma_f32 v[18:19], v[18:19], v[74:75], v[118:119]
	global_store_dwordx4 v[152:153], v[60:63], off offset:512
	global_store_dwordx4 v[152:153], v[56:59], off offset:528
	global_store_dwordx4 v[154:155], v[52:55], off offset:512
	global_store_dwordx4 v[154:155], v[48:51], off offset:528
	global_store_dwordx4 v[156:157], v[44:47], off offset:512
	global_store_dwordx4 v[156:157], v[40:43], off offset:528
	global_store_dwordx4 v[158:159], v[36:39], off offset:512
	global_store_dwordx4 v[158:159], v[32:35], off offset:528
	global_store_dwordx4 v[160:161], v[28:31], off offset:512
	global_store_dwordx4 v[160:161], v[24:27], off offset:528
	v_pk_fma_f32 v[16:17], v[16:17], v[72:73], v[116:117]
	global_store_dwordx4 v[162:163], v[20:23], off offset:512
	global_store_dwordx4 v[162:163], v[16:19], off offset:528
	v_pk_fma_f32 v[10:11], v[10:11], v[74:75], v[126:127]
	v_pk_fma_f32 v[8:9], v[8:9], v[72:73], v[124:125]
	global_store_dwordx4 v[164:165], v[12:15], off offset:512
	global_store_dwordx4 v[164:165], v[8:11], off offset:528
	s_waitcnt vmcnt(14)
	v_pk_fma_f32 v[2:3], v[2:3], v[74:75], v[134:135]
	v_pk_fma_f32 v[0:1], v[0:1], v[72:73], v[132:133]
	global_store_dwordx4 v[166:167], v[4:7], off offset:512
	global_store_dwordx4 v[166:167], v[0:3], off offset:528
	s_cbranch_vccnz .LBB9_841
	s_andn2_b64 vcc, exec, s[6:7]
	s_cbranch_vccnz .LBB9_840
	s_barrier
	s_branch .LBB9_840
